# layer-0 rms-norm row loop rewritten: gain vector loaded once, two rows per iteration with all loads in flight together, no per-quarter load/store round trips
# speedup vs baseline: 1.0042x; 1.0042x over previous
.LBB0_792:
	s_or_b64 exec, exec, s[18:19]
	s_cmpk_gt_i32 s10, 0x3fff
	s_cbranch_scc1 .LBB0_797
	s_load_dwordx2 s[0:1], s[14:15], 0x10
	v_lshlrev_b32_e32 v6, 4, v1
	s_waitcnt lgkmcnt(0)
	v_mov_b32_e32 v7, v0
	s_ashr_i32 s11, s10, 31
	v_readlane_b32 s6, v255, 14
	v_lshl_add_u64 v[18:19], s[0:1], 0, v[6:7]
	s_lshl_b64 s[0:1], s[10:11], 4
	s_add_u32 s6, s6, s82
	v_readlane_b32 s7, v255, 15
	s_addc_u32 s7, s7, s83
	s_add_u32 s0, s6, s0
	v_lshlrev_b32_e32 v2, 2, v1
	v_mov_b32_e32 v3, v0
	s_addc_u32 s1, s7, s1
	s_ashr_i32 s13, s12, 31
	v_lshl_add_u64 v[20:21], s[0:1], 0, v[2:3]
	s_lshl_b64 s[6:7], s[12:13], 4
	s_lshl_b64 s[0:1], s[10:11], 12
	s_add_u32 s0, s84, s0
	s_addc_u32 s1, s85, s1
	v_xor_b32_e32 v26, 4, v2
	v_xor_b32_e32 v27, 8, v2
	v_xor_b32_e32 v28, 16, v2
	v_xor_b32_e32 v29, 32, v2
	v_xor_b32_e32 v30, 64, v2
	v_xor_b32_e32 v31, 0x80, v2
	v_lshl_add_u64 v[2:3], s[0:1], 0, v[6:7]
	s_mov_b64 s[0:1], 0xc00
	v_lshl_add_u64 v[22:23], v[2:3], 0, s[0:1]
	s_lshl_b64 s[8:9], s[12:13], 12
	s_lshl_b64 s[0:1], s[10:11], 11
	v_readlane_b32 s11, v255, 16
	s_add_u32 s11, s11, s82
	v_readlane_b32 s14, v255, 17
	s_addc_u32 s14, s14, s83
	s_add_u32 s0, s11, s0
	v_mov_b32_e32 v5, v0
	s_addc_u32 s1, s14, s1
	v_cmp_gt_u32_e32 vcc, 4, v1
	v_cmp_eq_u32_e64 s[4:5], 0, v1
	v_lshl_add_u64 v[24:25], s[0:1], 0, v[4:5]
	s_lshl_b64 s[14:15], s[12:13], 11
	global_load_dwordx4 v[40:43], v[18:19], off
	global_load_dwordx4 v[44:47], v[18:19], off offset:1024
	global_load_dwordx4 v[48:51], v[18:19], off offset:2048
	global_load_dwordx4 v[52:55], v[18:19], off offset:3072
.Lrms_pair:
	global_load_dwordx4 v[14:17], v[22:23], off offset:-3072
	global_load_dwordx4 v[10:13], v[22:23], off offset:-2048
	global_load_dwordx4 v[6:9], v[22:23], off offset:-1024
	global_load_dwordx4 v[2:5], v[22:23], off
	s_add_i32 s0, s10, s12
	s_cmpk_gt_i32 s0, 0x3fff
	s_cselect_b32 s11, 0, 1
	s_cselect_b64 s[0:1], 0, s[8:9]
	v_lshl_add_u64 v[56:57], v[22:23], 0, s[0:1]
	global_load_dwordx4 v[72:75], v[56:57], off offset:-3072
	global_load_dwordx4 v[68:71], v[56:57], off offset:-2048
	global_load_dwordx4 v[64:67], v[56:57], off offset:-1024
	global_load_dwordx4 v[60:63], v[56:57], off
	v_lshl_add_u64 v[58:59], v[20:21], 0, s[6:7]
	v_lshl_add_u64 v[76:77], v[24:25], 0, s[14:15]
	s_waitcnt vmcnt(4)
	v_mul_f32_e32 v1, v14, v14
	v_mul_f32_e32 v32, v10, v10
	v_mul_f32_e32 v33, v6, v6
	v_mul_f32_e32 v34, v2, v2
	v_fmac_f32_e32 v1, v15, v15
	v_fmac_f32_e32 v32, v11, v11
	v_fmac_f32_e32 v33, v7, v7
	v_fmac_f32_e32 v34, v3, v3
	v_fmac_f32_e32 v1, v16, v16
	v_fmac_f32_e32 v32, v12, v12
	v_fmac_f32_e32 v33, v8, v8
	v_fmac_f32_e32 v34, v4, v4
	v_fmac_f32_e32 v1, v17, v17
	v_fmac_f32_e32 v32, v13, v13
	v_fmac_f32_e32 v33, v9, v9
	v_fmac_f32_e32 v34, v5, v5
	v_add_f32_e32 v1, v1, v32
	v_add_f32_e32 v33, v33, v34
	v_add_f32_e32 v1, v1, v33
	s_waitcnt vmcnt(0)
	v_mul_f32_e32 v36, v72, v72
	v_mul_f32_e32 v37, v68, v68
	v_mul_f32_e32 v38, v64, v64
	v_mul_f32_e32 v39, v60, v60
	v_fmac_f32_e32 v36, v73, v73
	v_fmac_f32_e32 v37, v69, v69
	v_fmac_f32_e32 v38, v65, v65
	v_fmac_f32_e32 v39, v61, v61
	v_fmac_f32_e32 v36, v74, v74
	v_fmac_f32_e32 v37, v70, v70
	v_fmac_f32_e32 v38, v66, v66
	v_fmac_f32_e32 v39, v62, v62
	v_fmac_f32_e32 v36, v75, v75
	v_fmac_f32_e32 v37, v71, v71
	v_fmac_f32_e32 v38, v67, v67
	v_fmac_f32_e32 v39, v63, v63
	v_add_f32_e32 v36, v36, v37
	v_add_f32_e32 v38, v38, v39
	v_add_f32_e32 v36, v36, v38
	ds_bpermute_b32 v32, v26, v1
	ds_bpermute_b32 v37, v26, v36
	s_waitcnt lgkmcnt(0)
	v_add_f32_e32 v1, v1, v32
	v_add_f32_e32 v36, v36, v37
	ds_bpermute_b32 v32, v27, v1
	ds_bpermute_b32 v37, v27, v36
	s_waitcnt lgkmcnt(0)
	v_add_f32_e32 v1, v1, v32
	v_add_f32_e32 v36, v36, v37
	ds_bpermute_b32 v32, v28, v1
	ds_bpermute_b32 v37, v28, v36
	s_waitcnt lgkmcnt(0)
	v_add_f32_e32 v1, v1, v32
	v_add_f32_e32 v36, v36, v37
	ds_bpermute_b32 v32, v29, v1
	ds_bpermute_b32 v37, v29, v36
	s_waitcnt lgkmcnt(0)
	v_add_f32_e32 v1, v1, v32
	v_add_f32_e32 v36, v36, v37
	ds_bpermute_b32 v32, v30, v1
	ds_bpermute_b32 v37, v30, v36
	s_waitcnt lgkmcnt(0)
	v_add_f32_e32 v1, v1, v32
	v_add_f32_e32 v36, v36, v37
	ds_bpermute_b32 v32, v31, v1
	ds_bpermute_b32 v37, v31, v36
	s_waitcnt lgkmcnt(0)
	v_add_f32_e32 v1, v1, v32
	v_add_f32_e32 v36, v36, v37
	s_and_saveexec_b64 s[16:17], vcc
	v_cndmask_b32_e64 v32, 0, v1, s[4:5]
	global_store_dword v[20:21], v32, off
	s_cmp_eq_u32 s11, 0
	s_cbranch_scc1 .Lrms_nob1
	v_cndmask_b32_e64 v37, 0, v36, s[4:5]
	global_store_dword v[58:59], v37, off
.Lrms_nob1:
	s_or_b64 exec, exec, s[16:17]
	v_pk_mul_f32 v[14:15], v[14:15], v[40:41]
	v_pk_mul_f32 v[16:17], v[16:17], v[42:43]
	v_pk_mul_f32 v[10:11], v[10:11], v[44:45]
	v_pk_mul_f32 v[12:13], v[12:13], v[46:47]
	v_pk_mul_f32 v[6:7], v[6:7], v[48:49]
	v_pk_mul_f32 v[8:9], v[8:9], v[50:51]
	v_pk_mul_f32 v[2:3], v[2:3], v[52:53]
	v_pk_mul_f32 v[4:5], v[4:5], v[54:55]
	v_cvt_pk_bf16_f32 v14, v14, v15
	v_cvt_pk_bf16_f32 v15, v16, v17
	v_cvt_pk_bf16_f32 v10, v10, v11
	v_cvt_pk_bf16_f32 v11, v12, v13
	v_cvt_pk_bf16_f32 v6, v6, v7
	v_cvt_pk_bf16_f32 v7, v8, v9
	v_cvt_pk_bf16_f32 v2, v2, v3
	v_cvt_pk_bf16_f32 v3, v4, v5
	global_store_dwordx2 v[24:25], v[14:15], off offset:-1024
	global_store_dwordx2 v[24:25], v[10:11], off offset:-512
	global_store_dwordx2 v[24:25], v[6:7], off
	global_store_dwordx2 v[24:25], v[2:3], off offset:512
	s_cmp_eq_u32 s11, 0
	s_cbranch_scc1 .Lrms_nob2
	v_pk_mul_f32 v[72:73], v[72:73], v[40:41]
	v_pk_mul_f32 v[74:75], v[74:75], v[42:43]
	v_pk_mul_f32 v[68:69], v[68:69], v[44:45]
	v_pk_mul_f32 v[70:71], v[70:71], v[46:47]
	v_pk_mul_f32 v[64:65], v[64:65], v[48:49]
	v_pk_mul_f32 v[66:67], v[66:67], v[50:51]
	v_pk_mul_f32 v[60:61], v[60:61], v[52:53]
	v_pk_mul_f32 v[62:63], v[62:63], v[54:55]
	v_cvt_pk_bf16_f32 v72, v72, v73
	v_cvt_pk_bf16_f32 v73, v74, v75
	v_cvt_pk_bf16_f32 v68, v68, v69
	v_cvt_pk_bf16_f32 v69, v70, v71
	v_cvt_pk_bf16_f32 v64, v64, v65
	v_cvt_pk_bf16_f32 v65, v66, v67
	v_cvt_pk_bf16_f32 v60, v60, v61
	v_cvt_pk_bf16_f32 v61, v62, v63
	global_store_dwordx2 v[76:77], v[72:73], off offset:-1024
	global_store_dwordx2 v[76:77], v[68:69], off offset:-512
	global_store_dwordx2 v[76:77], v[64:65], off
	global_store_dwordx2 v[76:77], v[60:61], off offset:512
.Lrms_nob2:
	s_add_i32 s10, s10, s12
	s_add_i32 s10, s10, s12
	v_lshl_add_u64 v[20:21], v[58:59], 0, s[6:7]
	v_lshl_add_u64 v[22:23], v[22:23], 0, s[8:9]
	v_lshl_add_u64 v[22:23], v[22:23], 0, s[8:9]
	v_lshl_add_u64 v[24:25], v[76:77], 0, s[14:15]
	s_cmpk_gt_i32 s10, 0x3fff
	s_cbranch_scc0 .Lrms_pair
